# layer-1 KV-cache conversion (HBM-bound, longer than one tail slot) split over the hl=1 and hl=2 G1 tails; hl=1 runs the general batched filler copy; G3(l=0) tail also converts the first 1400 GU1(l1) i
# baseline (speedup 1.0000x reference)
.LBB0_127:
	v_readlane_b32 s4, v253, 12
	v_readlane_b32 s5, v253, 13
	s_mov_b64 s[0:1], s[76:77]
	v_mov_b32_e32 v0, v204
	s_andn2_b64 vcc, exec, s[4:5]
	s_cbranch_vccnz .LBB0_251
	v_ashrrev_i32_e32 v2, 6, v0
	v_readlane_b32 s4, v253, 14
	s_nop 1
	v_add_u32_e32 v11, s4, v2
	s_movk_i32 s96, 0x1920
	s_movk_i32 s97, 0xa00
	s_cmp_eq_u32 s75, 3
	s_cselect_b32 s96, 0, s96
	s_cmp_eq_u32 s75, 1
	s_cselect_b32 s96, 0x1768, s96
	s_cselect_b32 s97, 0x588, s97
	v_cmp_gt_i32_e32 vcc, s96, v11
	s_and_saveexec_b64 s[24:25], vcc
	s_cbranch_execz .LBB0_250
	v_and_b32_e32 v10, 63, v0
	v_bfe_u32 v12, v0, 3, 3
	v_lshlrev_b32_e32 v3, 2, v0
	v_lshlrev_b32_e32 v0, 3, v0
	v_and_b32_e32 v14, 28, v3
	s_movk_i32 s4, 0x84
	v_mov_b32_e32 v3, 0x840
	v_and_b32_e32 v16, 56, v0
	v_lshl_add_u32 v2, v2, 14, 0
	v_mad_u32_u24 v29, v12, s4, v3
	v_mul_u32_u24_e32 v0, 0x84, v16
	v_lshlrev_b32_e32 v3, 2, v12
	v_lshl_add_u32 v15, v14, 2, v2
	v_mul_u32_u24_e32 v17, 0x84, v12
	v_or_b32_e32 v26, 8, v12
	v_mad_u32_u24 v27, v12, s4, v252
	v_or_b32_e32 v28, 16, v12
	v_or_b32_e32 v30, 24, v12
	v_or_b32_e32 v31, 32, v12
	v_or_b32_e32 v32, 40, v12
	v_or_b32_e32 v33, 48, v12
	v_or_b32_e32 v34, 56, v12
	v_add3_u32 v35, v2, v0, v3
	v_mov_b32_e32 v13, v1
	s_mov_b64 s[46:47], 0
	s_branch .LBB0_134

.LBB0_134:
	s_mov_b32 s4, 0xffffc300
	s_movk_i32 s5, 0x7e0
	s_cmp_eq_u32 s75, 1
	s_cselect_b32 s4, 0xffffbd78, s4
	s_cselect_b32 s5, 0xfffffa78, s5
	v_mov_b32_e32 v120, s5
	v_mov_b32_e32 v121, s4
	v_cmp_gt_i32_e32 vcc, s97, v11
	s_nop 0
	s_nop 0
	v_cndmask_b32_e32 v120, v120, v121, vcc
	v_add_u32_e32 v120, v120, v11
	s_movk_i32 s4, 0xdeff
	v_cmp_lt_i32_e32 vcc, s4, v120
	s_and_saveexec_b64 s[4:5], vcc
	s_xor_b64 s[40:41], exec, s[4:5]
	s_cbranch_execz .LBB0_170
	v_subrev_co_u32_e32 v0, vcc, 0xffffdf00, v120
	s_movk_i32 s4, 0xdeff
	s_mov_b64 s[38:39], vcc
	v_cmp_lt_u32_e32 vcc, s4, v120
	s_movk_i32 s4, 0x1080
	s_nop 0
	v_cndmask_b32_e32 v0, v120, v0, vcc
	v_add_u32_e32 v2, 0xef80, v0
	v_cmp_gt_u32_e32 vcc, s4, v0
	s_mov_b32 s4, 0xf83f
	s_nop 0
	v_cndmask_b32_e32 v3, v2, v0, vcc
	v_mul_u32_u24_sdwa v2, v3, s4 dst_sel:DWORD dst_unused:UNUSED_PAD src0_sel:WORD_0 src1_sel:DWORD
	v_lshrrev_b32_e32 v2, 25, v2
	v_mul_lo_u16_e32 v4, 0x210, v2
	v_sub_u16_e32 v3, v3, v4
	v_and_b32_e32 v4, 0x3fc, v3
	s_movk_i32 s4, 0x200
	v_cmp_ne_u32_e32 vcc, s4, v4
	s_and_saveexec_b64 s[42:43], vcc
	s_cbranch_execz .LBB0_169
	s_movk_i32 s4, 0x107f
	v_cmp_lt_u32_e32 vcc, s4, v0
	v_and_b32_e32 v20, 0xffff, v2
	s_movk_i32 s4, 0x200
	v_cndmask_b32_e64 v21, 0, 1, vcc
	v_lshlrev_b32_e32 v0, 3, v21
	global_load_dwordx2 v[18:19], v0, s[0:1] offset:32
	v_cndmask_b32_e64 v0, 0, 8, s[38:39]
	v_add_lshl_u32 v0, v0, v20, 23
	v_mov_b32_e32 v2, 0
	v_cmp_gt_u16_e32 vcc, s4, v3
	v_lshlrev_b32_e32 v8, 4, v10
	v_mov_b32_e32 v4, 0
	v_mov_b32_e32 v5, 0
	v_mov_b32_e32 v6, 0
	v_mov_b32_e32 v7, 0
	s_waitcnt vmcnt(0)
	v_lshl_add_u64 v[18:19], v[18:19], 0, v[0:1]
	v_lshlrev_b32_e32 v0, 14, v3
	v_lshl_add_u64 v[24:25], v[18:19], 0, v[0:1]
	s_and_saveexec_b64 s[48:49], vcc
	s_cbranch_execz .LBB0_138
	v_mov_b32_e32 v9, v1
	v_lshl_add_u64 v[4:5], v[24:25], 0, v[8:9]
	global_load_dwordx4 v[4:7], v[4:5], off

.LBB0_902:
	v_readlane_b32 s0, v254, 21
	v_readlane_b32 s1, v254, 22
	s_mov_b64 s[24:25], s[76:77]
	v_mov_b32_e32 v0, v204
	s_andn2_b64 vcc, exec, s[0:1]
	s_cbranch_vccnz .LBB0_1025
	v_ashrrev_i32_e32 v2, 6, v0
	v_readlane_b32 s0, v254, 23
	s_nop 1
	v_add_u32_e32 v11, s0, v2
	s_movk_i32 s0, 0x1200
	s_cmp_eq_u32 s64, 0
	s_cselect_b32 s0, 0x1778, s0
	v_cmp_gt_i32_e32 vcc, s0, v11
	s_and_saveexec_b64 s[44:45], vcc
	s_cbranch_execz .LBB0_1024
	v_and_b32_e32 v10, 63, v0
	v_bfe_u32 v12, v0, 3, 3
	v_lshlrev_b32_e32 v3, 2, v0
	v_lshlrev_b32_e32 v0, 3, v0
	v_and_b32_e32 v14, 28, v3
	s_movk_i32 s0, 0x84
	v_mov_b32_e32 v3, 0x840
	v_and_b32_e32 v16, 56, v0
	v_lshl_add_u32 v2, v2, 14, 0
	v_mad_u32_u24 v29, v12, s0, v3
	v_mul_u32_u24_e32 v0, 0x84, v16
	v_lshlrev_b32_e32 v3, 2, v12
	v_lshl_add_u32 v15, v14, 2, v2
	v_mul_u32_u24_e32 v17, 0x84, v12
	v_or_b32_e32 v26, 8, v12
	v_mad_u32_u24 v27, v12, s0, v252
	v_or_b32_e32 v28, 16, v12
	v_or_b32_e32 v30, 24, v12
	v_or_b32_e32 v31, 32, v12
	v_or_b32_e32 v32, 40, v12
	v_or_b32_e32 v33, 48, v12
	v_or_b32_e32 v34, 56, v12
	v_add3_u32 v35, v2, v0, v3
	v_mov_b32_e32 v13, v1
	s_mov_b64 s[46:47], 0
	s_branch .LBB0_908

.LBB0_907:
	s_or_b64 exec, exec, s[48:49]
	v_readlane_b32 s0, v254, 24
	s_nop 1
	v_add_u32_e32 v11, s0, v11
	s_movk_i32 s0, 0x11ff
	s_cmp_eq_u32 s64, 0
	s_cselect_b32 s0, 0x1777, s0
	v_cmp_lt_i32_e32 vcc, s0, v11
	s_or_b64 s[46:47], vcc, s[46:47]
	s_andn2_b64 exec, exec, s[46:47]
	s_cbranch_execz .LBB0_1024
